# c18 + attention M-block end: s_setprio 0 moved behind the barrier and the redundant lgkmcnt(0) wait removed (4 sites)
# speedup vs baseline: 1.0024x; 1.0024x over previous
; #define ATT_SBAR() __builtin_amdgcn_sched_barrier(0)
; #define QP_LD(d, s) do { ka[s] = *reinterpret_cast<const bf16x8*>(r0 + (d) * 32); kb[s] = *reinterpret_cast<const bf16x8*>(r1 + (d) * 32); } while (0)
; #define ATT_TRB(vb, off) __builtin_amdgcn_ds_read_tr16_b64_v4i16((LAS s16x4*)(unsigned)((vb) + (off)))
; #define VMWAIT() asm volatile("s_waitcnt vmcnt(0)" ::: "memory")
; template <int DK> __device__ __forceinline__ void qkt_pipe_pv(f32x16& p0, f32x16& p1, const char* Ks, const bf16x8* qr, int r32, int hi, int vb, s16x4 (&F)[8]) {
;     constexpr int ND = DK / 16, KR = DK * 2 + 16;
;     const char* r0 = Ks + ATT_KSWZ(r32, hi * 16, KR); const char* r1 = Ks + ATT_KSWZ(32 + r32, hi * 16, KR);
;     bf16x8 ka[3], kb[3];
;     ...
;     QP_LD(0, 0); QP_LD(1, 1); QP_LD(2, 2); ATT_SBAR();
;     p0 = f32x16{}; p1 = f32x16{};
;     __builtin_amdgcn_s_setprio(1);
; #pragma unroll
;     for (int d0 = 0; d0 < ND; ++d0) {
;         p0 = __builtin_amdgcn_mfma_f32_32x32x16_bf16(ka[d0 % 3], qr[d0], p0, 0, 0, 0);
;         p1 = __builtin_amdgcn_mfma_f32_32x32x16_bf16(kb[d0 % 3], qr[d0], p1, 0, 0, 0);
;         if (d0 + 3 < ND) QP_LD(d0 + 3, d0 % 3);
;         if (d0 == ND - 3) { F[0] = ATT_TRB(vb, v_rd_off(0, 0, 0)); F[1] = ATT_TRB(vb, v_rd_off(0, 0, 1)); F[2] = ATT_TRB(vb, v_rd_off(0, 1, 0)); F[3] = ATT_TRB(vb, v_rd_off(0, 1, 1)); }
;         if (d0 == ND - 2) { F[4] = ATT_TRB(vb, v_rd_off(0, 2, 0)); F[5] = ATT_TRB(vb, v_rd_off(0, 2, 1)); F[6] = ATT_TRB(vb, v_rd_off(0, 3, 0)); F[7] = ATT_TRB(vb, v_rd_off(0, 3, 1)); }
;         ATT_SBAR(); }
;     __builtin_amdgcn_s_setprio(0);
;     ...
; }
; __device__ __forceinline__ void pv_d0_pre(f32x16* o, int vb, bf16x8 pa0, bf16x8 pa1, bf16x8 pa2, bf16x8 pa3, s16x4 (&F)[8]) {
;     s16x4 G[8];
;     ...
;     PVB_RD(1, G); ATT_SBAR(); PVB_MM(0, F); ATT_SBAR();
;     PVB_RD(2, F); ATT_SBAR(); PVB_MM(1, G); ATT_SBAR();
;     PVB_RD(3, G); ATT_SBAR(); PVB_MM(2, F); ATT_SBAR();
;     PVB_MM(3, G);
;     ...
; }
; template <int DK, bool CAUSAL> ...
;     ...
;     f32x16 p0, p1; float mn, al; bf16x8 pa0, pa1, pa2, pa3;
;     KLOAD(KVBLK); { const bf16x8 t0 = ks0, t1 = ks1, t2 = kr0;
;       KLOAD(0); VLOAD(0); VMWAIT(); KWRITE(0); VWRITE(0);
;       ks0 = t0; ks1 = t1; if constexpr (DK == 192) kr0 = t2; KWRITE(SHM_K); }
;     PPBAR();
;     { const int kt0 = 1 + half, vt0 = half; if (kt0 < NT) KLOAD(kt0 * KVBLK); if (vt0 < NT) VLOAD(vt0 * KVBLK); }
;     if (half == 1) PPBAR();
.LBB0_803:
	v_lshlrev_b32_e32 v18, 4, v202
	v_lshlrev_b32_e32 v0, 3, v202
	v_and_b32_e32 v18, 0xc0, v18
	v_lshlrev_b32_e32 v19, 1, v202
	v_and_or_b32 v18, v0, 24, v18
	v_and_b32_e32 v19, 32, v19
	v_and_b32_e32 v0, 0x100, v0
	v_or3_b32 v0, v18, v19, v0
	s_waitcnt lgkmcnt(0)
	s_barrier
	v_add_u32_e32 v198, 0xe400, v195
	ds_read_b128 v[18:21], v195 offset:58368
	ds_read_b128 v[22:25], v195 offset:58400
	ds_read_b128 v[26:29], v198 offset:12800
	ds_read_b128 v[30:33], v195 offset:58432
	ds_read_b128 v[34:37], v198 offset:12832
	ds_read_b128 v[38:41], v198 offset:12864
	s_setprio 1
	s_waitcnt lgkmcnt(5)
	v_mfma_f32_32x32x16_bf16 v[82:97], v[18:21], v[98:101], 0
	ds_read_b128 v[18:21], v195 offset:58464
	ds_read_b128 v[42:45], v198 offset:12896
	s_cmp_lg_u32 0, -1
	s_cselect_b32 s0, 0, 0
	s_waitcnt lgkmcnt(5)
	v_mfma_f32_32x32x16_bf16 v[66:81], v[26:29], v[98:101], 0
	v_mfma_f32_32x32x16_bf16 v[82:97], v[22:25], v[102:105], v[82:97]
	ds_read_b128 v[22:25], v195 offset:58496
	ds_read_b128 v[26:29], v198 offset:12928
	s_waitcnt lgkmcnt(5)
	v_mfma_f32_32x32x16_bf16 v[66:81], v[34:37], v[102:105], v[66:81]
	v_mfma_f32_32x32x16_bf16 v[82:97], v[30:33], v[106:109], v[82:97]
	ds_read_b128 v[30:33], v195 offset:58528
	ds_read_b128 v[34:37], v198 offset:12960
	s_waitcnt lgkmcnt(6)
	v_mfma_f32_32x32x16_bf16 v[66:81], v[38:41], v[106:109], v[66:81]
	s_waitcnt lgkmcnt(5)
	v_mfma_f32_32x32x16_bf16 v[82:97], v[18:21], v[110:113], v[82:97]
	ds_read_b128 v[18:21], v195 offset:58560
	ds_read_b128 v[38:41], v198 offset:12992
	s_waitcnt lgkmcnt(6)
	v_mfma_f32_32x32x16_bf16 v[66:81], v[42:45], v[110:113], v[66:81]
	s_waitcnt lgkmcnt(5)
	v_mfma_f32_32x32x16_bf16 v[82:97], v[22:25], v[114:117], v[82:97]
	ds_read_b128 v[22:25], v195 offset:58592
	ds_read_b128 v[42:45], v198 offset:13024
	s_waitcnt lgkmcnt(6)
	v_mfma_f32_32x32x16_bf16 v[66:81], v[26:29], v[114:117], v[66:81]
	s_waitcnt lgkmcnt(5)
	v_mfma_f32_32x32x16_bf16 v[82:97], v[30:33], v[118:121], v[82:97]
	ds_read_b128 v[26:29], v195 offset:58624
	ds_read_b128 v[30:33], v198 offset:13056
	s_waitcnt lgkmcnt(6)
	v_mfma_f32_32x32x16_bf16 v[66:81], v[34:37], v[118:121], v[66:81]
	s_waitcnt lgkmcnt(5)
	v_mfma_f32_32x32x16_bf16 v[82:97], v[18:21], v[122:125], v[82:97]
	ds_read_b128 v[18:21], v195 offset:58656
	ds_read_b128 v[34:37], v198 offset:13088
	s_waitcnt lgkmcnt(6)
	v_mfma_f32_32x32x16_bf16 v[66:81], v[38:41], v[122:125], v[66:81]
	s_waitcnt lgkmcnt(5)
	v_mfma_f32_32x32x16_bf16 v[82:97], v[22:25], v[126:129], v[82:97]
	ds_read_b128 v[22:25], v195 offset:58688
	ds_read_b128 v[38:41], v198 offset:13120
	s_waitcnt lgkmcnt(6)
	v_mfma_f32_32x32x16_bf16 v[66:81], v[42:45], v[126:129], v[66:81]
	s_waitcnt lgkmcnt(5)
	v_mfma_f32_32x32x16_bf16 v[82:97], v[26:29], v[130:133], v[82:97]
	ds_read_b128 v[26:29], v195 offset:58720
	ds_read_b128 v[42:45], v198 offset:13152
	s_waitcnt lgkmcnt(6)
	v_mfma_f32_32x32x16_bf16 v[66:81], v[30:33], v[130:133], v[66:81]
	s_waitcnt lgkmcnt(5)
	v_mfma_f32_32x32x16_bf16 v[82:97], v[18:21], v[158:161], v[82:97]
	v_add_u32_e32 v197, 0, v0
	v_add_u32_e32 v0, s0, v0
	ds_read_b64_tr_b16 v[46:47], v197
	ds_read_b64_tr_b16 v[48:49], v0 offset:2048
	ds_read_b64_tr_b16 v[50:51], v0 offset:4096
	ds_read_b64_tr_b16 v[52:53], v0 offset:6144
	s_waitcnt lgkmcnt(8)
	v_mfma_f32_32x32x16_bf16 v[66:81], v[34:37], v[158:161], v[66:81]
	s_waitcnt lgkmcnt(7)
	v_mfma_f32_32x32x16_bf16 v[82:97], v[22:25], v[134:137], v[82:97]
	ds_read_b64_tr_b16 v[34:35], v0 offset:8192
	ds_read_b64_tr_b16 v[36:37], v0 offset:10240
	ds_read_b64_tr_b16 v[54:55], v0 offset:12288
	ds_read_b64_tr_b16 v[56:57], v0 offset:14336
	s_waitcnt lgkmcnt(10)
	v_mfma_f32_32x32x16_bf16 v[66:81], v[38:41], v[134:137], v[66:81]
	s_waitcnt lgkmcnt(9)
	v_mfma_f32_32x32x16_bf16 v[82:97], v[26:29], v[162:165], v[82:97]
	s_waitcnt lgkmcnt(8)
	v_mfma_f32_32x32x16_bf16 v[66:81], v[42:45], v[162:165], v[66:81]
	s_setprio 0
	ds_read_b64_tr_b16 v[58:59], v0 offset:512
	ds_read_b64_tr_b16 v[60:61], v0 offset:2560
	ds_read_b64_tr_b16 v[62:63], v0 offset:4608
	ds_read_b64_tr_b16 v[64:65], v0 offset:6656
	ds_read_b64_tr_b16 v[206:207], v0 offset:8704
	ds_read_b64_tr_b16 v[208:209], v0 offset:10752
	ds_read_b64_tr_b16 v[210:211], v0 offset:12800
	ds_read_b64_tr_b16 v[212:213], v0 offset:14848
	s_setprio 1
	s_waitcnt lgkmcnt(14)
	v_mfma_f32_32x32x16_bf16 v[18:33], v[166:169], v[46:49], v[2:17]
	s_waitcnt lgkmcnt(12)
	v_mfma_f32_32x32x16_bf16 v[18:33], v[170:173], v[50:53], v[18:33]
	s_waitcnt lgkmcnt(10)
	v_mfma_f32_32x32x16_bf16 v[18:33], v[174:177], v[34:37], v[18:33]
	s_waitcnt lgkmcnt(8)
	v_mfma_f32_32x32x16_bf16 v[18:33], v[178:181], v[54:57], v[18:33]
	s_setprio 0
	ds_read_b64_tr_b16 v[214:215], v0 offset:1024
	ds_read_b64_tr_b16 v[216:217], v0 offset:3072
	ds_read_b64_tr_b16 v[218:219], v0 offset:5120
	ds_read_b64_tr_b16 v[220:221], v0 offset:7168
	ds_read_b64_tr_b16 v[222:223], v0 offset:9216
	ds_read_b64_tr_b16 v[224:225], v0 offset:11264
	ds_read_b64_tr_b16 v[226:227], v0 offset:13312
	ds_read_b64_tr_b16 v[228:229], v0 offset:15360
	s_setprio 1
	s_waitcnt lgkmcnt(14)
	v_mfma_f32_32x32x16_bf16 v[34:49], v[166:169], v[58:61], v[2:17]
	s_waitcnt lgkmcnt(12)
	v_mfma_f32_32x32x16_bf16 v[34:49], v[170:173], v[62:65], v[34:49]
	s_waitcnt lgkmcnt(10)
	v_mfma_f32_32x32x16_bf16 v[34:49], v[174:177], v[206:209], v[34:49]
	s_waitcnt lgkmcnt(8)
	v_mfma_f32_32x32x16_bf16 v[34:49], v[178:181], v[210:213], v[34:49]
	s_setprio 0
	ds_read_b64_tr_b16 v[206:207], v0 offset:1536
	ds_read_b64_tr_b16 v[208:209], v0 offset:3584
	ds_read_b64_tr_b16 v[210:211], v0 offset:5632
	ds_read_b64_tr_b16 v[212:213], v0 offset:7680
	ds_read_b64_tr_b16 v[230:231], v0 offset:9728
	ds_read_b64_tr_b16 v[232:233], v0 offset:11776
	ds_read_b64_tr_b16 v[234:235], v0 offset:13824
	ds_read_b64_tr_b16 v[236:237], v0 offset:15872
	s_setprio 1
	s_waitcnt lgkmcnt(14)
	v_mfma_f32_32x32x16_bf16 v[50:65], v[166:169], v[214:217], v[2:17]
	s_waitcnt lgkmcnt(12)
	v_mfma_f32_32x32x16_bf16 v[50:65], v[170:173], v[218:221], v[50:65]
	s_waitcnt lgkmcnt(10)
	v_mfma_f32_32x32x16_bf16 v[50:65], v[174:177], v[222:225], v[50:65]
	s_waitcnt lgkmcnt(8)
	v_mfma_f32_32x32x16_bf16 v[50:65], v[178:181], v[226:229], v[50:65]
	s_setprio 0
	s_setprio 1
	s_waitcnt lgkmcnt(6)
	v_mfma_f32_32x32x16_bf16 v[2:17], v[166:169], v[206:209], v[2:17]
	s_waitcnt lgkmcnt(4)
	v_mfma_f32_32x32x16_bf16 v[2:17], v[170:173], v[210:213], v[2:17]
	s_waitcnt lgkmcnt(2)
	v_mfma_f32_32x32x16_bf16 v[2:17], v[174:177], v[230:233], v[2:17]
	s_waitcnt lgkmcnt(0)
	v_mfma_f32_32x32x16_bf16 v[2:17], v[178:181], v[234:237], v[2:17]
	s_barrier
; __device__ __forceinline__ int crow(int r, int hi) { return (r & 3) + 8 * (r >> 2) + 4 * hi; }
; __device__ __forceinline__ void cmask(f32x16& p0, f32x16& p1, int t, int qrel, int hi) {
;     const float ninf = -__builtin_inff();
; #pragma unroll
;     for (int r = 0; r < 16; ++r) { const int k0 = 64 * t + crow(r, hi); if (k0 > qrel) p0[r] = ninf; if (k0 + 32 > qrel) p1[r] = ninf; }
; }
	s_setprio 0
	s_cmp_lt_i32 s82, 4
	s_cselect_b64 s[0:1], -1, 0
	s_and_b64 s[0:1], s[66:67], s[0:1]
	s_andn2_b64 vcc, exec, s[0:1]
	s_cbranch_vccnz .LBB0_805
	v_or_b32_e32 v166, 0x60, v196
	v_or_b32_e32 v0, 64, v196
	v_cmp_le_i32_e32 vcc, v166, v203
	s_nop 1
	v_cndmask_b32_e32 v66, v190, v66, vcc
	v_cmp_lt_i32_e32 vcc, v0, v203
	s_nop 1
	v_cndmask_b32_e32 v83, v190, v83, vcc
	v_cmp_le_i32_e32 vcc, v0, v203
	v_or_b32_e32 v0, 0x61, v196
	s_nop 0
	v_cndmask_b32_e32 v82, v190, v82, vcc
	v_cmp_le_i32_e32 vcc, v0, v203
	v_or_b32_e32 v0, 0x42, v196
	s_nop 0
	v_cndmask_b32_e32 v67, v190, v67, vcc
	v_cmp_le_i32_e32 vcc, v0, v203
	v_or_b32_e32 v0, 0x62, v196
	s_nop 0
	v_cndmask_b32_e32 v84, v190, v84, vcc
	v_cmp_le_i32_e32 vcc, v0, v203
	v_or_b32_e32 v0, 0x43, v196
	s_nop 0
	v_cndmask_b32_e32 v68, v190, v68, vcc
	v_cmp_le_i32_e32 vcc, v0, v203
	v_or_b32_e32 v0, 0x63, v196
	s_nop 0
	v_cndmask_b32_e32 v85, v190, v85, vcc
	v_cmp_le_i32_e32 vcc, v0, v203
	v_or_b32_e32 v0, 0x48, v196
	s_nop 0
	v_cndmask_b32_e32 v69, v190, v69, vcc
	v_cmp_le_i32_e32 vcc, v0, v203
	v_or_b32_e32 v0, 0x68, v196
	s_nop 0
	v_cndmask_b32_e32 v86, v190, v86, vcc
	v_cmp_le_i32_e32 vcc, v0, v203
	v_or_b32_e32 v0, 0x49, v196
	s_nop 0
	v_cndmask_b32_e32 v70, v190, v70, vcc
	v_cmp_le_i32_e32 vcc, v0, v203
	v_or_b32_e32 v0, 0x69, v196
	s_nop 0
	v_cndmask_b32_e32 v87, v190, v87, vcc
	v_cmp_le_i32_e32 vcc, v0, v203
	v_or_b32_e32 v0, 0x4a, v196
	s_nop 0
	v_cndmask_b32_e32 v71, v190, v71, vcc
	v_cmp_le_i32_e32 vcc, v0, v203
	v_or_b32_e32 v0, 0x6a, v196
	s_nop 0
	v_cndmask_b32_e32 v88, v190, v88, vcc
	v_cmp_le_i32_e32 vcc, v0, v203
	v_or_b32_e32 v0, 0x4b, v196
	s_nop 0
	v_cndmask_b32_e32 v72, v190, v72, vcc
	v_cmp_le_i32_e32 vcc, v0, v203
	v_or_b32_e32 v0, 0x6b, v196
	s_nop 0
	v_cndmask_b32_e32 v89, v190, v89, vcc
	v_cmp_le_i32_e32 vcc, v0, v203
	v_or_b32_e32 v0, 0x50, v196
	s_nop 0
	v_cndmask_b32_e32 v73, v190, v73, vcc
	v_cmp_le_i32_e32 vcc, v0, v203
	v_or_b32_e32 v0, 0x70, v196
	s_nop 0
	v_cndmask_b32_e32 v90, v190, v90, vcc
	v_cmp_le_i32_e32 vcc, v0, v203
	v_or_b32_e32 v0, 0x51, v196
	s_nop 0
	v_cndmask_b32_e32 v74, v190, v74, vcc
	v_cmp_le_i32_e32 vcc, v0, v203
	v_or_b32_e32 v0, 0x71, v196
	s_nop 0
	v_cndmask_b32_e32 v91, v190, v91, vcc
	v_cmp_le_i32_e32 vcc, v0, v203
	v_or_b32_e32 v0, 0x52, v196
	s_nop 0
	v_cndmask_b32_e32 v75, v190, v75, vcc
	v_cmp_le_i32_e32 vcc, v0, v203
	v_or_b32_e32 v0, 0x72, v196
	s_nop 0
	v_cndmask_b32_e32 v92, v190, v92, vcc
	v_cmp_le_i32_e32 vcc, v0, v203
	v_or_b32_e32 v0, 0x53, v196
	s_nop 0
	v_cndmask_b32_e32 v76, v190, v76, vcc
	v_cmp_le_i32_e32 vcc, v0, v203
	v_or_b32_e32 v0, 0x73, v196
	s_nop 0
	v_cndmask_b32_e32 v93, v190, v93, vcc
	v_cmp_le_i32_e32 vcc, v0, v203
	v_or_b32_e32 v0, 0x58, v196
	s_nop 0
	v_cndmask_b32_e32 v77, v190, v77, vcc
	v_cmp_le_i32_e32 vcc, v0, v203
	v_or_b32_e32 v0, 0x78, v196
	s_nop 0
	v_cndmask_b32_e32 v94, v190, v94, vcc
	v_cmp_le_i32_e32 vcc, v0, v203
	v_or_b32_e32 v0, 0x59, v196
	s_nop 0
	v_cndmask_b32_e32 v78, v190, v78, vcc
	v_cmp_le_i32_e32 vcc, v0, v203
	v_or_b32_e32 v0, 0x79, v196
	s_nop 0
	v_cndmask_b32_e32 v95, v190, v95, vcc
	v_cmp_le_i32_e32 vcc, v0, v203
	v_or_b32_e32 v0, 0x5a, v196
	s_nop 0
	v_cndmask_b32_e32 v79, v190, v79, vcc
	v_cmp_le_i32_e32 vcc, v0, v203
	v_or_b32_e32 v0, 0x7a, v196
	s_nop 0
	v_cndmask_b32_e32 v96, v190, v96, vcc
	v_cmp_le_i32_e32 vcc, v0, v203
	v_or_b32_e32 v0, 0x5b, v196
	s_nop 0
	v_cndmask_b32_e32 v80, v190, v80, vcc
	v_cmp_le_i32_e32 vcc, v0, v203
	v_or_b32_e32 v0, 0x7b, v196
	s_nop 0
	v_cndmask_b32_e32 v97, v190, v97, vcc
	v_cmp_le_i32_e32 vcc, v0, v203
	s_nop 1
	v_cndmask_b32_e32 v81, v190, v81, vcc

; #define ATT_SBAR() __builtin_amdgcn_sched_barrier(0)
; #define QP_LD(d, s) do { ka[s] = *reinterpret_cast<const bf16x8*>(r0 + (d) * 32); kb[s] = *reinterpret_cast<const bf16x8*>(r1 + (d) * 32); } while (0)
; #define ATT_TRB(vb, off) __builtin_amdgcn_ds_read_tr16_b64_v4i16((LAS s16x4*)(unsigned)((vb) + (off)))
; #define VMWAIT() asm volatile("s_waitcnt vmcnt(0)" ::: "memory")
; template <int DK> __device__ __forceinline__ void qkt_pipe_pv(f32x16& p0, f32x16& p1, const char* Ks, const bf16x8* qr, int r32, int hi, int vb, s16x4 (&F)[8]) {
;     constexpr int ND = DK / 16, KR = DK * 2 + 16;
;     const char* r0 = Ks + ATT_KSWZ(r32, hi * 16, KR); const char* r1 = Ks + ATT_KSWZ(32 + r32, hi * 16, KR);
;     bf16x8 ka[3], kb[3];
;     ...
;     QP_LD(0, 0); QP_LD(1, 1); QP_LD(2, 2); ATT_SBAR();
;     p0 = f32x16{}; p1 = f32x16{};
;     __builtin_amdgcn_s_setprio(1);
; #pragma unroll
;     for (int d0 = 0; d0 < ND; ++d0) {
;         p0 = __builtin_amdgcn_mfma_f32_32x32x16_bf16(ka[d0 % 3], qr[d0], p0, 0, 0, 0);
;         p1 = __builtin_amdgcn_mfma_f32_32x32x16_bf16(kb[d0 % 3], qr[d0], p1, 0, 0, 0);
;         if (d0 + 3 < ND) QP_LD(d0 + 3, d0 % 3);
;         if (d0 == ND - 3) { F[0] = ATT_TRB(vb, v_rd_off(0, 0, 0)); F[1] = ATT_TRB(vb, v_rd_off(0, 0, 1)); F[2] = ATT_TRB(vb, v_rd_off(0, 1, 0)); F[3] = ATT_TRB(vb, v_rd_off(0, 1, 1)); }
;         if (d0 == ND - 2) { F[4] = ATT_TRB(vb, v_rd_off(0, 2, 0)); F[5] = ATT_TRB(vb, v_rd_off(0, 2, 1)); F[6] = ATT_TRB(vb, v_rd_off(0, 3, 0)); F[7] = ATT_TRB(vb, v_rd_off(0, 3, 1)); }
;         ATT_SBAR(); }
;     __builtin_amdgcn_s_setprio(0);
;     ...
; }
; __device__ __forceinline__ void pv_d0_pre(f32x16* o, int vb, bf16x8 pa0, bf16x8 pa1, bf16x8 pa2, bf16x8 pa3, s16x4 (&F)[8]) {
;     s16x4 G[8];
;     ...
;     PVB_RD(1, G); ATT_SBAR(); PVB_MM(0, F); ATT_SBAR();
;     PVB_RD(2, F); ATT_SBAR(); PVB_MM(1, G); ATT_SBAR();
;     PVB_RD(3, G); ATT_SBAR(); PVB_MM(2, F); ATT_SBAR();
;     PVB_MM(3, G);
;     ...
; }
; template <int DK, bool CAUSAL> ...
;     ...
;     f32x16 p0, p1; float mn, al; bf16x8 pa0, pa1, pa2, pa3;
;     KLOAD(KVBLK); { const bf16x8 t0 = ks0, t1 = ks1, t2 = kr0;
;       KLOAD(0); VLOAD(0); VMWAIT(); KWRITE(0); VWRITE(0);
;       ks0 = t0; ks1 = t1; if constexpr (DK == 192) kr0 = t2; KWRITE(SHM_K); }
;     PPBAR();
;     { const int kt0 = 1 + half, vt0 = half; if (kt0 < NT) KLOAD(kt0 * KVBLK); if (vt0 < NT) VLOAD(vt0 * KVBLK); }
;     if (half == 1) PPBAR();
.LBB0_819:
	ds_read_b128 v[66:69], v195 offset:32768
	ds_read_b128 v[204:207], v195 offset:32800
	ds_read_b128 v[70:73], v195 offset:45568
	ds_read_b128 v[208:211], v195 offset:32832
	ds_read_b128 v[212:215], v195 offset:45600
	ds_read_b128 v[216:219], v195 offset:45632
	s_setprio 1
	s_waitcnt lgkmcnt(5)
	v_mfma_f32_32x32x16_bf16 v[82:97], v[66:69], v[98:101], 0
	ds_read_b128 v[220:223], v195 offset:32864
	ds_read_b128 v[224:227], v195 offset:45664
	s_waitcnt lgkmcnt(5)
	v_mfma_f32_32x32x16_bf16 v[66:81], v[70:73], v[98:101], 0
	v_mfma_f32_32x32x16_bf16 v[82:97], v[204:207], v[102:105], v[82:97]
	ds_read_b128 v[204:207], v195 offset:32896
	ds_read_b128 v[228:231], v195 offset:45696
	s_waitcnt lgkmcnt(5)
	v_mfma_f32_32x32x16_bf16 v[66:81], v[212:215], v[102:105], v[66:81]
	v_mfma_f32_32x32x16_bf16 v[82:97], v[208:211], v[106:109], v[82:97]
	ds_read_b128 v[208:211], v195 offset:32928
	ds_read_b128 v[212:215], v195 offset:45728
	s_waitcnt lgkmcnt(6)
	v_mfma_f32_32x32x16_bf16 v[66:81], v[216:219], v[106:109], v[66:81]
	s_waitcnt lgkmcnt(5)
	v_mfma_f32_32x32x16_bf16 v[82:97], v[220:223], v[110:113], v[82:97]
	ds_read_b128 v[216:219], v195 offset:32960
	ds_read_b128 v[220:223], v195 offset:45760
	s_waitcnt lgkmcnt(6)
	v_mfma_f32_32x32x16_bf16 v[66:81], v[224:227], v[110:113], v[66:81]
	s_waitcnt lgkmcnt(5)
	v_mfma_f32_32x32x16_bf16 v[82:97], v[204:207], v[114:117], v[82:97]
	ds_read_b128 v[204:207], v195 offset:32992
	ds_read_b128 v[224:227], v195 offset:45792
	s_waitcnt lgkmcnt(6)
	v_mfma_f32_32x32x16_bf16 v[66:81], v[228:231], v[114:117], v[66:81]
	s_waitcnt lgkmcnt(5)
	v_mfma_f32_32x32x16_bf16 v[82:97], v[208:211], v[118:121], v[82:97]
	ds_read_b128 v[208:211], v195 offset:33024
	ds_read_b128 v[228:231], v195 offset:45824
	s_waitcnt lgkmcnt(6)
	v_mfma_f32_32x32x16_bf16 v[66:81], v[212:215], v[118:121], v[66:81]
	s_waitcnt lgkmcnt(5)
	v_mfma_f32_32x32x16_bf16 v[82:97], v[216:219], v[122:125], v[82:97]
	ds_read_b128 v[212:215], v195 offset:33056
	ds_read_b128 v[216:219], v195 offset:45856
	s_waitcnt lgkmcnt(6)
	v_mfma_f32_32x32x16_bf16 v[66:81], v[220:223], v[122:125], v[66:81]
	s_waitcnt lgkmcnt(5)
	v_mfma_f32_32x32x16_bf16 v[82:97], v[204:207], v[126:129], v[82:97]
	ds_read_b128 v[204:207], v195 offset:33088
	ds_read_b128 v[220:223], v195 offset:45888
	s_waitcnt lgkmcnt(6)
	v_mfma_f32_32x32x16_bf16 v[66:81], v[224:227], v[126:129], v[66:81]
	s_waitcnt lgkmcnt(5)
	v_mfma_f32_32x32x16_bf16 v[82:97], v[208:211], v[130:133], v[82:97]
	ds_read_b128 v[208:211], v195 offset:33120
	ds_read_b128 v[224:227], v195 offset:45920
	s_waitcnt lgkmcnt(6)
	v_mfma_f32_32x32x16_bf16 v[66:81], v[228:231], v[130:133], v[66:81]
	s_waitcnt lgkmcnt(5)
	v_mfma_f32_32x32x16_bf16 v[82:97], v[212:215], v[158:161], v[82:97]
	ds_read_b64_tr_b16 v[212:213], v197 offset:16384
	ds_read_b64_tr_b16 v[214:215], v197 offset:18432
	ds_read_b64_tr_b16 v[228:229], v197 offset:20480
	ds_read_b64_tr_b16 v[230:231], v197 offset:22528
	s_waitcnt lgkmcnt(8)
	v_mfma_f32_32x32x16_bf16 v[66:81], v[216:219], v[158:161], v[66:81]
	s_waitcnt lgkmcnt(7)
	v_mfma_f32_32x32x16_bf16 v[82:97], v[204:207], v[134:137], v[82:97]
	ds_read_b64_tr_b16 v[204:205], v197 offset:24576
	ds_read_b64_tr_b16 v[206:207], v197 offset:26624
	ds_read_b64_tr_b16 v[216:217], v197 offset:28672
	ds_read_b64_tr_b16 v[218:219], v197 offset:30720
	s_waitcnt lgkmcnt(10)
	v_mfma_f32_32x32x16_bf16 v[66:81], v[220:223], v[134:137], v[66:81]
	s_waitcnt lgkmcnt(9)
	v_mfma_f32_32x32x16_bf16 v[82:97], v[208:211], v[162:165], v[82:97]
	s_waitcnt lgkmcnt(8)
	v_mfma_f32_32x32x16_bf16 v[66:81], v[224:227], v[162:165], v[66:81]
	s_setprio 0
	ds_read_b64_tr_b16 v[208:209], v197 offset:16896
	ds_read_b64_tr_b16 v[210:211], v197 offset:18944
	ds_read_b64_tr_b16 v[220:221], v197 offset:20992
	ds_read_b64_tr_b16 v[222:223], v197 offset:23040
	ds_read_b64_tr_b16 v[224:225], v197 offset:25088
	ds_read_b64_tr_b16 v[226:227], v197 offset:27136
	ds_read_b64_tr_b16 v[232:233], v197 offset:29184
	ds_read_b64_tr_b16 v[234:235], v197 offset:31232
	s_setprio 1
	s_waitcnt lgkmcnt(14)
	v_mfma_f32_32x32x16_bf16 v[18:33], v[166:169], v[212:215], v[18:33]
	s_waitcnt lgkmcnt(12)
	v_mfma_f32_32x32x16_bf16 v[18:33], v[170:173], v[228:231], v[18:33]
	s_waitcnt lgkmcnt(10)
	v_mfma_f32_32x32x16_bf16 v[18:33], v[174:177], v[204:207], v[18:33]
	s_waitcnt lgkmcnt(8)
	v_mfma_f32_32x32x16_bf16 v[18:33], v[178:181], v[216:219], v[18:33]
	s_setprio 0
	ds_read_b64_tr_b16 v[204:205], v197 offset:17408
	ds_read_b64_tr_b16 v[206:207], v197 offset:19456
	ds_read_b64_tr_b16 v[212:213], v197 offset:21504
	ds_read_b64_tr_b16 v[214:215], v197 offset:23552
	ds_read_b64_tr_b16 v[216:217], v197 offset:25600
	ds_read_b64_tr_b16 v[218:219], v197 offset:27648
	ds_read_b64_tr_b16 v[228:229], v197 offset:29696
	ds_read_b64_tr_b16 v[230:231], v197 offset:31744
	s_setprio 1
	s_waitcnt lgkmcnt(14)
	v_mfma_f32_32x32x16_bf16 v[34:49], v[166:169], v[208:211], v[34:49]
	s_waitcnt lgkmcnt(12)
	v_mfma_f32_32x32x16_bf16 v[34:49], v[170:173], v[220:223], v[34:49]
	s_waitcnt lgkmcnt(10)
	v_mfma_f32_32x32x16_bf16 v[34:49], v[174:177], v[224:227], v[34:49]
	s_waitcnt lgkmcnt(8)
	v_mfma_f32_32x32x16_bf16 v[34:49], v[178:181], v[232:235], v[34:49]
	s_setprio 0
	ds_read_b64_tr_b16 v[208:209], v197 offset:17920
	ds_read_b64_tr_b16 v[210:211], v197 offset:19968
	ds_read_b64_tr_b16 v[220:221], v197 offset:22016
	ds_read_b64_tr_b16 v[222:223], v197 offset:24064
	ds_read_b64_tr_b16 v[224:225], v197 offset:26112
	ds_read_b64_tr_b16 v[226:227], v197 offset:28160
	ds_read_b64_tr_b16 v[232:233], v197 offset:30208
	ds_read_b64_tr_b16 v[234:235], v197 offset:32256
	s_setprio 1
	s_waitcnt lgkmcnt(14)
	v_mfma_f32_32x32x16_bf16 v[50:65], v[166:169], v[204:207], v[50:65]
	s_waitcnt lgkmcnt(12)
	v_mfma_f32_32x32x16_bf16 v[50:65], v[170:173], v[212:215], v[50:65]
	s_waitcnt lgkmcnt(10)
	v_mfma_f32_32x32x16_bf16 v[50:65], v[174:177], v[216:219], v[50:65]
	s_waitcnt lgkmcnt(8)
	v_mfma_f32_32x32x16_bf16 v[50:65], v[178:181], v[228:231], v[50:65]
	s_setprio 0
	s_setprio 1
	s_waitcnt lgkmcnt(6)
	v_mfma_f32_32x32x16_bf16 v[2:17], v[166:169], v[208:211], v[2:17]
	s_waitcnt lgkmcnt(4)
	v_mfma_f32_32x32x16_bf16 v[2:17], v[170:173], v[220:223], v[2:17]
	s_waitcnt lgkmcnt(2)
	v_mfma_f32_32x32x16_bf16 v[2:17], v[174:177], v[224:227], v[2:17]
	s_waitcnt lgkmcnt(0)
	v_mfma_f32_32x32x16_bf16 v[2:17], v[178:181], v[232:235], v[2:17]
	s_barrier
; __device__ __forceinline__ int crow(int r, int hi) { return (r & 3) + 8 * (r >> 2) + 4 * hi; }
; __device__ __forceinline__ void cmask(f32x16& p0, f32x16& p1, int t, int qrel, int hi) {
;     const float ninf = -__builtin_inff();
; #pragma unroll
;     for (int r = 0; r < 16; ++r) { const int k0 = 64 * t + crow(r, hi); if (k0 > qrel) p0[r] = ninf; if (k0 + 32 > qrel) p1[r] = ninf; }
; }
	s_setprio 0
	s_add_i32 s8, s90, s86
	s_cmp_lt_i32 s8, 0
	s_cbranch_scc1 .LBB0_822
	s_sub_i32 s0, s58, 64
	s_cmp_le_i32 s0, s83
	s_cbranch_scc1 .LBB0_822
	v_add_u32_e32 v0, s58, v196
	v_add_u32_e32 v167, 0xffffffa1, v0
	v_add_u32_e32 v166, 0xffffff81, v0
	v_cmp_le_i32_e32 vcc, v167, v200
	s_nop 1
	v_cndmask_b32_e32 v66, v190, v66, vcc
	v_cmp_lt_i32_e32 vcc, v166, v200
	s_nop 1
	v_cndmask_b32_e32 v83, v190, v83, vcc
	v_cmp_le_i32_e32 vcc, v166, v200
	v_add_u32_e32 v166, 0xffffffa2, v0
	s_nop 0
	v_cndmask_b32_e32 v82, v190, v82, vcc
	v_cmp_le_i32_e32 vcc, v166, v200
	v_add_u32_e32 v166, 0xffffff83, v0
	s_nop 0
	v_cndmask_b32_e32 v67, v190, v67, vcc
	v_cmp_le_i32_e32 vcc, v166, v200
	v_add_u32_e32 v166, 0xffffffa3, v0
	s_nop 0
	v_cndmask_b32_e32 v84, v190, v84, vcc
	v_cmp_le_i32_e32 vcc, v166, v200
	v_add_u32_e32 v166, 0xffffff84, v0
	s_nop 0
	v_cndmask_b32_e32 v68, v190, v68, vcc
	v_cmp_le_i32_e32 vcc, v166, v200
	v_add_u32_e32 v166, 0xffffffa4, v0
	s_nop 0
	v_cndmask_b32_e32 v85, v190, v85, vcc
	v_cmp_le_i32_e32 vcc, v166, v200
	v_add_u32_e32 v166, 0xffffff89, v0
	s_nop 0
	v_cndmask_b32_e32 v69, v190, v69, vcc
	v_cmp_le_i32_e32 vcc, v166, v200
	v_add_u32_e32 v166, 0xffffffa9, v0
	s_nop 0
	v_cndmask_b32_e32 v86, v190, v86, vcc
	v_cmp_le_i32_e32 vcc, v166, v200
	v_add_u32_e32 v166, 0xffffff8a, v0
	s_nop 0
	v_cndmask_b32_e32 v70, v190, v70, vcc
	v_cmp_le_i32_e32 vcc, v166, v200
	v_add_u32_e32 v166, 0xffffffaa, v0
	s_nop 0
	v_cndmask_b32_e32 v87, v190, v87, vcc
	v_cmp_le_i32_e32 vcc, v166, v200
	v_add_u32_e32 v166, 0xffffff8b, v0
	s_nop 0
	v_cndmask_b32_e32 v71, v190, v71, vcc
	v_cmp_le_i32_e32 vcc, v166, v200
	v_add_u32_e32 v166, 0xffffffab, v0
	s_nop 0
	v_cndmask_b32_e32 v88, v190, v88, vcc
	v_cmp_le_i32_e32 vcc, v166, v200
	v_add_u32_e32 v166, 0xffffff8c, v0
	s_nop 0
	v_cndmask_b32_e32 v72, v190, v72, vcc
	v_cmp_le_i32_e32 vcc, v166, v200
	v_add_u32_e32 v166, 0xffffffac, v0
	s_nop 0
	v_cndmask_b32_e32 v89, v190, v89, vcc
	v_cmp_le_i32_e32 vcc, v166, v200
	v_add_u32_e32 v166, 0xffffff91, v0
	s_nop 0
	v_cndmask_b32_e32 v73, v190, v73, vcc
	v_cmp_le_i32_e32 vcc, v166, v200
	v_add_u32_e32 v166, 0xffffffb1, v0
	s_nop 0
	v_cndmask_b32_e32 v90, v190, v90, vcc
	v_cmp_le_i32_e32 vcc, v166, v200
	v_add_u32_e32 v166, 0xffffff92, v0
	s_nop 0
	v_cndmask_b32_e32 v74, v190, v74, vcc
	v_cmp_le_i32_e32 vcc, v166, v200
	v_add_u32_e32 v166, 0xffffffb2, v0
	s_nop 0
	v_cndmask_b32_e32 v91, v190, v91, vcc
	v_cmp_le_i32_e32 vcc, v166, v200
	v_add_u32_e32 v166, 0xffffff93, v0
	s_nop 0
	v_cndmask_b32_e32 v75, v190, v75, vcc
	v_cmp_le_i32_e32 vcc, v166, v200
	v_add_u32_e32 v166, 0xffffffb3, v0
	s_nop 0
	v_cndmask_b32_e32 v92, v190, v92, vcc
	v_cmp_le_i32_e32 vcc, v166, v200
	v_add_u32_e32 v166, 0xffffff94, v0
	s_nop 0
	v_cndmask_b32_e32 v76, v190, v76, vcc
	v_cmp_le_i32_e32 vcc, v166, v200
	v_add_u32_e32 v166, 0xffffffb4, v0
	s_nop 0
	v_cndmask_b32_e32 v93, v190, v93, vcc
	v_cmp_le_i32_e32 vcc, v166, v200
	v_add_u32_e32 v166, 0xffffff99, v0
	s_nop 0
	v_cndmask_b32_e32 v77, v190, v77, vcc
	v_cmp_le_i32_e32 vcc, v166, v200
	v_add_u32_e32 v166, 0xffffffb9, v0
	s_nop 0
	v_cndmask_b32_e32 v94, v190, v94, vcc
	v_cmp_le_i32_e32 vcc, v166, v200
	v_add_u32_e32 v166, 0xffffff9a, v0
	s_nop 0
	v_cndmask_b32_e32 v78, v190, v78, vcc
	v_cmp_le_i32_e32 vcc, v166, v200
	v_add_u32_e32 v166, 0xffffffba, v0
	s_nop 0
	v_cndmask_b32_e32 v95, v190, v95, vcc
	v_cmp_le_i32_e32 vcc, v166, v200
	v_add_u32_e32 v166, 0xffffff9b, v0
	s_nop 0
	v_cndmask_b32_e32 v79, v190, v79, vcc
	v_cmp_le_i32_e32 vcc, v166, v200
	v_add_u32_e32 v166, 0xffffffbb, v0
	s_nop 0
	v_cndmask_b32_e32 v96, v190, v96, vcc
	v_cmp_le_i32_e32 vcc, v166, v200
	v_add_u32_e32 v166, 0xffffff9c, v0
	v_add_u32_e32 v0, 0xffffffbc, v0
	v_cndmask_b32_e32 v80, v190, v80, vcc
	v_cmp_le_i32_e32 vcc, v166, v200
	s_nop 1
	v_cndmask_b32_e32 v97, v190, v97, vcc
	v_cmp_le_i32_e32 vcc, v0, v200
	s_nop 1
	v_cndmask_b32_e32 v81, v190, v81, vcc

; #define ATT_SBAR() __builtin_amdgcn_sched_barrier(0)
; #define QP_LD(d, s) do { ka[s] = *reinterpret_cast<const bf16x8*>(r0 + (d) * 32); kb[s] = *reinterpret_cast<const bf16x8*>(r1 + (d) * 32); } while (0)
; #define ATT_TRB(vb, off) __builtin_amdgcn_ds_read_tr16_b64_v4i16((LAS s16x4*)(unsigned)((vb) + (off)))
; #define VMWAIT() asm volatile("s_waitcnt vmcnt(0)" ::: "memory")
; template <int DK> __device__ __forceinline__ void qkt_pipe_pv(f32x16& p0, f32x16& p1, const char* Ks, const bf16x8* qr, int r32, int hi, int vb, s16x4 (&F)[8]) {
;     constexpr int ND = DK / 16, KR = DK * 2 + 16;
;     const char* r0 = Ks + ATT_KSWZ(r32, hi * 16, KR); const char* r1 = Ks + ATT_KSWZ(32 + r32, hi * 16, KR);
;     bf16x8 ka[3], kb[3];
;     ...
;     QP_LD(0, 0); QP_LD(1, 1); QP_LD(2, 2); ATT_SBAR();
;     p0 = f32x16{}; p1 = f32x16{};
;     __builtin_amdgcn_s_setprio(1);
; #pragma unroll
;     for (int d0 = 0; d0 < ND; ++d0) {
;         p0 = __builtin_amdgcn_mfma_f32_32x32x16_bf16(ka[d0 % 3], qr[d0], p0, 0, 0, 0);
;         p1 = __builtin_amdgcn_mfma_f32_32x32x16_bf16(kb[d0 % 3], qr[d0], p1, 0, 0, 0);
;         if (d0 + 3 < ND) QP_LD(d0 + 3, d0 % 3);
;         if (d0 == ND - 3) { F[0] = ATT_TRB(vb, v_rd_off(0, 0, 0)); F[1] = ATT_TRB(vb, v_rd_off(0, 0, 1)); F[2] = ATT_TRB(vb, v_rd_off(0, 1, 0)); F[3] = ATT_TRB(vb, v_rd_off(0, 1, 1)); }
;         if (d0 == ND - 2) { F[4] = ATT_TRB(vb, v_rd_off(0, 2, 0)); F[5] = ATT_TRB(vb, v_rd_off(0, 2, 1)); F[6] = ATT_TRB(vb, v_rd_off(0, 3, 0)); F[7] = ATT_TRB(vb, v_rd_off(0, 3, 1)); }
;         ATT_SBAR(); }
;     __builtin_amdgcn_s_setprio(0);
;     ...
; }
; __device__ __forceinline__ void pv_d0_pre(f32x16* o, int vb, bf16x8 pa0, bf16x8 pa1, bf16x8 pa2, bf16x8 pa3, s16x4 (&F)[8]) {
;     s16x4 G[8];
;     ...
;     PVB_RD(1, G); ATT_SBAR(); PVB_MM(0, F); ATT_SBAR();
;     PVB_RD(2, F); ATT_SBAR(); PVB_MM(1, G); ATT_SBAR();
;     PVB_RD(3, G); ATT_SBAR(); PVB_MM(2, F); ATT_SBAR();
;     PVB_MM(3, G);
;     ...
; }
; template <int DK, bool CAUSAL> ...
;     ...
;     f32x16 p0, p1; float mn, al; bf16x8 pa0, pa1, pa2, pa3;
;     KLOAD(KVBLK); { const bf16x8 t0 = ks0, t1 = ks1, t2 = kr0;
;       KLOAD(0); VLOAD(0); VMWAIT(); KWRITE(0); VWRITE(0);
;       ks0 = t0; ks1 = t1; if constexpr (DK == 192) kr0 = t2; KWRITE(SHM_K); }
;     PPBAR();
;     { const int kt0 = 1 + half, vt0 = half; if (kt0 < NT) KLOAD(kt0 * KVBLK); if (vt0 < NT) VLOAD(vt0 * KVBLK); }
;     if (half == 1) PPBAR();
.LBB0_834:
	s_waitcnt lgkmcnt(0)
	s_barrier
	ds_read_b128 v[66:69], v195 offset:58368
	ds_read_b128 v[206:209], v195 offset:58400
	ds_read_b128 v[70:73], v198 offset:12800
	ds_read_b128 v[210:213], v195 offset:58432
	ds_read_b128 v[214:217], v198 offset:12832
	ds_read_b128 v[218:221], v198 offset:12864
	s_setprio 1
	s_waitcnt lgkmcnt(5)
	v_mfma_f32_32x32x16_bf16 v[82:97], v[66:69], v[98:101], 0
	ds_read_b128 v[222:225], v195 offset:58464
	ds_read_b128 v[226:229], v198 offset:12896
	s_waitcnt lgkmcnt(5)
	v_mfma_f32_32x32x16_bf16 v[66:81], v[70:73], v[98:101], 0
	v_mfma_f32_32x32x16_bf16 v[82:97], v[206:209], v[102:105], v[82:97]
	ds_read_b128 v[206:209], v195 offset:58496
	ds_read_b128 v[230:233], v198 offset:12928
	s_waitcnt lgkmcnt(5)
	v_mfma_f32_32x32x16_bf16 v[66:81], v[214:217], v[102:105], v[66:81]
	v_mfma_f32_32x32x16_bf16 v[82:97], v[210:213], v[106:109], v[82:97]
	ds_read_b128 v[210:213], v195 offset:58528
	ds_read_b128 v[214:217], v198 offset:12960
	s_waitcnt lgkmcnt(6)
	v_mfma_f32_32x32x16_bf16 v[66:81], v[218:221], v[106:109], v[66:81]
	s_waitcnt lgkmcnt(5)
	v_mfma_f32_32x32x16_bf16 v[82:97], v[222:225], v[110:113], v[82:97]
	ds_read_b128 v[218:221], v195 offset:58560
	ds_read_b128 v[222:225], v198 offset:12992
	s_waitcnt lgkmcnt(6)
	v_mfma_f32_32x32x16_bf16 v[66:81], v[226:229], v[110:113], v[66:81]
	s_waitcnt lgkmcnt(5)
	v_mfma_f32_32x32x16_bf16 v[82:97], v[206:209], v[114:117], v[82:97]
	ds_read_b128 v[206:209], v195 offset:58592
	ds_read_b128 v[226:229], v198 offset:13024
	s_waitcnt lgkmcnt(6)
	v_mfma_f32_32x32x16_bf16 v[66:81], v[230:233], v[114:117], v[66:81]
	s_waitcnt lgkmcnt(5)
	v_mfma_f32_32x32x16_bf16 v[82:97], v[210:213], v[118:121], v[82:97]
	ds_read_b128 v[210:213], v195 offset:58624
	ds_read_b128 v[230:233], v198 offset:13056
	s_waitcnt lgkmcnt(6)
	v_mfma_f32_32x32x16_bf16 v[66:81], v[214:217], v[118:121], v[66:81]
	s_waitcnt lgkmcnt(5)
	v_mfma_f32_32x32x16_bf16 v[82:97], v[218:221], v[122:125], v[82:97]
	ds_read_b128 v[214:217], v195 offset:58656
	ds_read_b128 v[218:221], v198 offset:13088
	s_waitcnt lgkmcnt(6)
	v_mfma_f32_32x32x16_bf16 v[66:81], v[222:225], v[122:125], v[66:81]
	s_waitcnt lgkmcnt(5)
	v_mfma_f32_32x32x16_bf16 v[82:97], v[206:209], v[126:129], v[82:97]
	ds_read_b128 v[206:209], v195 offset:58688
	ds_read_b128 v[222:225], v198 offset:13120
	s_waitcnt lgkmcnt(6)
	v_mfma_f32_32x32x16_bf16 v[66:81], v[226:229], v[126:129], v[66:81]
	s_waitcnt lgkmcnt(5)
	v_mfma_f32_32x32x16_bf16 v[82:97], v[210:213], v[130:133], v[82:97]
	ds_read_b128 v[210:213], v195 offset:58720
	ds_read_b128 v[226:229], v198 offset:13152
	s_waitcnt lgkmcnt(6)
	v_mfma_f32_32x32x16_bf16 v[66:81], v[230:233], v[130:133], v[66:81]
	s_waitcnt lgkmcnt(5)
	v_mfma_f32_32x32x16_bf16 v[82:97], v[214:217], v[158:161], v[82:97]
	ds_read_b64_tr_b16 v[214:215], v197
	ds_read_b64_tr_b16 v[216:217], v197 offset:2048
	ds_read_b64_tr_b16 v[230:231], v197 offset:4096
	ds_read_b64_tr_b16 v[232:233], v197 offset:6144
	s_waitcnt lgkmcnt(8)
	v_mfma_f32_32x32x16_bf16 v[66:81], v[218:221], v[158:161], v[66:81]
	s_waitcnt lgkmcnt(7)
	v_mfma_f32_32x32x16_bf16 v[82:97], v[206:209], v[134:137], v[82:97]
	ds_read_b64_tr_b16 v[206:207], v197 offset:8192
	ds_read_b64_tr_b16 v[208:209], v197 offset:10240
	ds_read_b64_tr_b16 v[218:219], v197 offset:12288
	ds_read_b64_tr_b16 v[220:221], v197 offset:14336
	s_waitcnt lgkmcnt(10)
	v_mfma_f32_32x32x16_bf16 v[66:81], v[222:225], v[134:137], v[66:81]
	s_waitcnt lgkmcnt(9)
	v_mfma_f32_32x32x16_bf16 v[82:97], v[210:213], v[162:165], v[82:97]
	s_waitcnt lgkmcnt(8)
	v_mfma_f32_32x32x16_bf16 v[66:81], v[226:229], v[162:165], v[66:81]
	s_setprio 0
	ds_read_b64_tr_b16 v[210:211], v197 offset:512
	ds_read_b64_tr_b16 v[212:213], v197 offset:2560
	ds_read_b64_tr_b16 v[222:223], v197 offset:4608
	ds_read_b64_tr_b16 v[224:225], v197 offset:6656
	ds_read_b64_tr_b16 v[226:227], v197 offset:8704
	ds_read_b64_tr_b16 v[228:229], v197 offset:10752
	ds_read_b64_tr_b16 v[234:235], v197 offset:12800
	ds_read_b64_tr_b16 v[236:237], v197 offset:14848
	s_setprio 1
	s_waitcnt lgkmcnt(14)
	v_mfma_f32_32x32x16_bf16 v[18:33], v[166:169], v[214:217], v[18:33]
	s_waitcnt lgkmcnt(12)
	v_mfma_f32_32x32x16_bf16 v[18:33], v[170:173], v[230:233], v[18:33]
	s_waitcnt lgkmcnt(10)
	v_mfma_f32_32x32x16_bf16 v[18:33], v[174:177], v[206:209], v[18:33]
	s_waitcnt lgkmcnt(8)
	v_mfma_f32_32x32x16_bf16 v[18:33], v[178:181], v[218:221], v[18:33]
	s_setprio 0
	ds_read_b64_tr_b16 v[206:207], v197 offset:1024
	ds_read_b64_tr_b16 v[208:209], v197 offset:3072
	ds_read_b64_tr_b16 v[214:215], v197 offset:5120
	ds_read_b64_tr_b16 v[216:217], v197 offset:7168
	ds_read_b64_tr_b16 v[218:219], v197 offset:9216
	ds_read_b64_tr_b16 v[220:221], v197 offset:11264
	ds_read_b64_tr_b16 v[230:231], v197 offset:13312
	ds_read_b64_tr_b16 v[232:233], v197 offset:15360
	s_setprio 1
	s_waitcnt lgkmcnt(14)
	v_mfma_f32_32x32x16_bf16 v[34:49], v[166:169], v[210:213], v[34:49]
	s_waitcnt lgkmcnt(12)
	v_mfma_f32_32x32x16_bf16 v[34:49], v[170:173], v[222:225], v[34:49]
	s_waitcnt lgkmcnt(10)
	v_mfma_f32_32x32x16_bf16 v[34:49], v[174:177], v[226:229], v[34:49]
	s_waitcnt lgkmcnt(8)
	v_mfma_f32_32x32x16_bf16 v[34:49], v[178:181], v[234:237], v[34:49]
	s_setprio 0
	ds_read_b64_tr_b16 v[210:211], v197 offset:1536
	ds_read_b64_tr_b16 v[212:213], v197 offset:3584
	ds_read_b64_tr_b16 v[222:223], v197 offset:5632
	ds_read_b64_tr_b16 v[224:225], v197 offset:7680
	ds_read_b64_tr_b16 v[226:227], v197 offset:9728
	ds_read_b64_tr_b16 v[228:229], v197 offset:11776
	ds_read_b64_tr_b16 v[234:235], v197 offset:13824
	ds_read_b64_tr_b16 v[236:237], v197 offset:15872
	s_setprio 1
	s_waitcnt lgkmcnt(14)
	v_mfma_f32_32x32x16_bf16 v[50:65], v[166:169], v[206:209], v[50:65]
	s_waitcnt lgkmcnt(12)
	v_mfma_f32_32x32x16_bf16 v[50:65], v[170:173], v[214:217], v[50:65]
	s_waitcnt lgkmcnt(10)
	v_mfma_f32_32x32x16_bf16 v[50:65], v[174:177], v[218:221], v[50:65]
	s_waitcnt lgkmcnt(8)
	v_mfma_f32_32x32x16_bf16 v[50:65], v[178:181], v[230:233], v[50:65]
	s_setprio 0
	s_setprio 1
	s_waitcnt lgkmcnt(6)
	v_mfma_f32_32x32x16_bf16 v[2:17], v[166:169], v[210:213], v[2:17]
	s_waitcnt lgkmcnt(4)
	v_mfma_f32_32x32x16_bf16 v[2:17], v[170:173], v[222:225], v[2:17]
	s_waitcnt lgkmcnt(2)
	v_mfma_f32_32x32x16_bf16 v[2:17], v[174:177], v[226:229], v[2:17]
	s_waitcnt lgkmcnt(0)
	v_mfma_f32_32x32x16_bf16 v[2:17], v[178:181], v[234:237], v[2:17]
	s_barrier
; __device__ __forceinline__ int crow(int r, int hi) { return (r & 3) + 8 * (r >> 2) + 4 * hi; }
; __device__ __forceinline__ void cmask(f32x16& p0, f32x16& p1, int t, int qrel, int hi) {
;     const float ninf = -__builtin_inff();
; #pragma unroll
;     for (int r = 0; r < 16; ++r) { const int k0 = 64 * t + crow(r, hi); if (k0 > qrel) p0[r] = ninf; if (k0 + 32 > qrel) p1[r] = ninf; }
; }
	s_setprio 0
	s_add_i32 s8, s8, 1
	s_cmp_lt_i32 s8, 0
	s_cbranch_scc1 .LBB0_837
	s_cmp_le_i32 s58, s83
	s_cbranch_scc1 .LBB0_837
	v_add_u32_e32 v0, s58, v196
	v_subrev_u32_e32 v167, 31, v0
	v_subrev_u32_e32 v166, 63, v0
	v_cmp_le_i32_e32 vcc, v167, v200
	s_nop 1
	v_cndmask_b32_e32 v66, v190, v66, vcc
	v_cmp_lt_i32_e32 vcc, v166, v200
	s_nop 1
	v_cndmask_b32_e32 v83, v190, v83, vcc
	v_cmp_le_i32_e32 vcc, v166, v200
	v_subrev_u32_e32 v166, 30, v0
	s_nop 0
	v_cndmask_b32_e32 v82, v190, v82, vcc
	v_cmp_le_i32_e32 vcc, v166, v200
	v_subrev_u32_e32 v166, 61, v0
	s_nop 0
	v_cndmask_b32_e32 v67, v190, v67, vcc
	v_cmp_le_i32_e32 vcc, v166, v200
	v_subrev_u32_e32 v166, 29, v0
	s_nop 0
	v_cndmask_b32_e32 v84, v190, v84, vcc
	v_cmp_le_i32_e32 vcc, v166, v200
	v_subrev_u32_e32 v166, 60, v0
	s_nop 0
	v_cndmask_b32_e32 v68, v190, v68, vcc
	v_cmp_le_i32_e32 vcc, v166, v200
	v_subrev_u32_e32 v166, 28, v0
	s_nop 0
	v_cndmask_b32_e32 v85, v190, v85, vcc
	v_cmp_le_i32_e32 vcc, v166, v200
	v_subrev_u32_e32 v166, 55, v0
	s_nop 0
	v_cndmask_b32_e32 v69, v190, v69, vcc
	v_cmp_le_i32_e32 vcc, v166, v200
	v_subrev_u32_e32 v166, 23, v0
	s_nop 0
	v_cndmask_b32_e32 v86, v190, v86, vcc
	v_cmp_le_i32_e32 vcc, v166, v200
	v_subrev_u32_e32 v166, 54, v0
	s_nop 0
	v_cndmask_b32_e32 v70, v190, v70, vcc
	v_cmp_le_i32_e32 vcc, v166, v200
	v_subrev_u32_e32 v166, 22, v0
	s_nop 0
	v_cndmask_b32_e32 v87, v190, v87, vcc
	v_cmp_le_i32_e32 vcc, v166, v200
	v_subrev_u32_e32 v166, 53, v0
	s_nop 0
	v_cndmask_b32_e32 v71, v190, v71, vcc
	v_cmp_le_i32_e32 vcc, v166, v200
	v_subrev_u32_e32 v166, 21, v0
	s_nop 0
	v_cndmask_b32_e32 v88, v190, v88, vcc
	v_cmp_le_i32_e32 vcc, v166, v200
	v_subrev_u32_e32 v166, 52, v0
	s_nop 0
	v_cndmask_b32_e32 v72, v190, v72, vcc
	v_cmp_le_i32_e32 vcc, v166, v200
	v_subrev_u32_e32 v166, 20, v0
	s_nop 0
	v_cndmask_b32_e32 v89, v190, v89, vcc
	v_cmp_le_i32_e32 vcc, v166, v200
	v_subrev_u32_e32 v166, 47, v0
	s_nop 0
	v_cndmask_b32_e32 v73, v190, v73, vcc
	v_cmp_le_i32_e32 vcc, v166, v200
	v_add_u32_e32 v166, -15, v0
	s_nop 0
	v_cndmask_b32_e32 v90, v190, v90, vcc
	v_cmp_le_i32_e32 vcc, v166, v200
	v_subrev_u32_e32 v166, 46, v0
	s_nop 0
	v_cndmask_b32_e32 v74, v190, v74, vcc
	v_cmp_le_i32_e32 vcc, v166, v200
	v_add_u32_e32 v166, -14, v0
	s_nop 0
	v_cndmask_b32_e32 v91, v190, v91, vcc
	v_cmp_le_i32_e32 vcc, v166, v200
	v_subrev_u32_e32 v166, 45, v0
	s_nop 0
	v_cndmask_b32_e32 v75, v190, v75, vcc
	v_cmp_le_i32_e32 vcc, v166, v200
	v_add_u32_e32 v166, -13, v0
	s_nop 0
	v_cndmask_b32_e32 v92, v190, v92, vcc
	v_cmp_le_i32_e32 vcc, v166, v200
	v_subrev_u32_e32 v166, 44, v0
	s_nop 0
	v_cndmask_b32_e32 v76, v190, v76, vcc
	v_cmp_le_i32_e32 vcc, v166, v200
	v_add_u32_e32 v166, -12, v0
	s_nop 0
	v_cndmask_b32_e32 v93, v190, v93, vcc
	v_cmp_le_i32_e32 vcc, v166, v200
	v_subrev_u32_e32 v166, 39, v0
	s_nop 0
	v_cndmask_b32_e32 v77, v190, v77, vcc
	v_cmp_le_i32_e32 vcc, v166, v200
	v_add_u32_e32 v166, -7, v0
	s_nop 0
	v_cndmask_b32_e32 v94, v190, v94, vcc
	v_cmp_le_i32_e32 vcc, v166, v200
	v_subrev_u32_e32 v166, 38, v0
	s_nop 0
	v_cndmask_b32_e32 v78, v190, v78, vcc
	v_cmp_le_i32_e32 vcc, v166, v200
	v_add_u32_e32 v166, -6, v0
	s_nop 0
	v_cndmask_b32_e32 v95, v190, v95, vcc
	v_cmp_le_i32_e32 vcc, v166, v200
	v_subrev_u32_e32 v166, 37, v0
	s_nop 0
	v_cndmask_b32_e32 v79, v190, v79, vcc
	v_cmp_le_i32_e32 vcc, v166, v200
	v_add_u32_e32 v166, -5, v0
	s_nop 0
	v_cndmask_b32_e32 v96, v190, v96, vcc
	v_cmp_le_i32_e32 vcc, v166, v200
	v_subrev_u32_e32 v166, 36, v0
	v_add_u32_e32 v0, -4, v0
	v_cndmask_b32_e32 v80, v190, v80, vcc
	v_cmp_le_i32_e32 vcc, v166, v200
	s_nop 1
	v_cndmask_b32_e32 v97, v190, v97, vcc
	v_cmp_le_i32_e32 vcc, v0, v200
	s_nop 1
	v_cndmask_b32_e32 v81, v190, v81, vcc

; #define ATT_SBAR() __builtin_amdgcn_sched_barrier(0)
; #define PV_RD(D0, X) do { X[0] = PV_TRB(v_rd_off(D0, 0, 0)); X[1] = PV_TRB(v_rd_off(D0, 0, 1)); X[2] = PV_TRB(v_rd_off(D0, 1, 0)); X[3] = PV_TRB(v_rd_off(D0, 1, 1)); \
;                           X[4] = PV_TRB(v_rd_off(D0, 2, 0)); X[5] = PV_TRB(v_rd_off(D0, 2, 1)); X[6] = PV_TRB(v_rd_off(D0, 3, 0)); X[7] = PV_TRB(v_rd_off(D0, 3, 1)); } while (0)
; __device__ __forceinline__ void pv_d0(f32x16* o, int vb, bf16x8 pa0, bf16x8 pa1, bf16x8 pa2, bf16x8 pa3) {
;     ...
;     s16x4 F[8], G[8];
;     PV_RD(0, F); ATT_SBAR();
;     PV_RD(1, G); ATT_SBAR(); PV_MM(0, F); ATT_SBAR();
;     PV_RD(2, F); ATT_SBAR(); PV_MM(1, G); ATT_SBAR();
;     PV_RD(3, G); ATT_SBAR(); PV_MM(2, F); ATT_SBAR();
;     PV_MM(3, G);
;     ...
; }
.LBB0_849:
	ds_read_b64_tr_b16 v[66:67], v197 offset:16384
	ds_read_b64_tr_b16 v[68:69], v197 offset:18432
	ds_read_b64_tr_b16 v[70:71], v197 offset:20480
	ds_read_b64_tr_b16 v[72:73], v197 offset:22528
	ds_read_b64_tr_b16 v[74:75], v197 offset:24576
	ds_read_b64_tr_b16 v[76:77], v197 offset:26624
	ds_read_b64_tr_b16 v[78:79], v197 offset:28672
	ds_read_b64_tr_b16 v[80:81], v197 offset:30720
	ds_read_b64_tr_b16 v[82:83], v197 offset:16896
	ds_read_b64_tr_b16 v[84:85], v197 offset:18944
	ds_read_b64_tr_b16 v[86:87], v197 offset:20992
	ds_read_b64_tr_b16 v[88:89], v197 offset:23040
	ds_read_b64_tr_b16 v[90:91], v197 offset:25088
	ds_read_b64_tr_b16 v[92:93], v197 offset:27136
	ds_read_b64_tr_b16 v[94:95], v197 offset:29184
	ds_read_b64_tr_b16 v[96:97], v197 offset:31232
	s_setprio 1
	s_waitcnt lgkmcnt(14)
	v_mfma_f32_32x32x16_bf16 v[18:33], v[166:169], v[66:69], v[18:33]
	s_waitcnt lgkmcnt(12)
	v_mfma_f32_32x32x16_bf16 v[18:33], v[170:173], v[70:73], v[18:33]
	s_waitcnt lgkmcnt(10)
	v_mfma_f32_32x32x16_bf16 v[18:33], v[174:177], v[74:77], v[18:33]
	s_waitcnt lgkmcnt(8)
	v_mfma_f32_32x32x16_bf16 v[18:33], v[178:181], v[78:81], v[18:33]
	s_setprio 0
	ds_read_b64_tr_b16 v[66:67], v197 offset:17408
	ds_read_b64_tr_b16 v[68:69], v197 offset:19456
	ds_read_b64_tr_b16 v[70:71], v197 offset:21504
	ds_read_b64_tr_b16 v[72:73], v197 offset:23552
	ds_read_b64_tr_b16 v[74:75], v197 offset:25600
	ds_read_b64_tr_b16 v[76:77], v197 offset:27648
	ds_read_b64_tr_b16 v[78:79], v197 offset:29696
	ds_read_b64_tr_b16 v[80:81], v197 offset:31744
	s_setprio 1
	s_waitcnt lgkmcnt(14)
	v_mfma_f32_32x32x16_bf16 v[34:49], v[166:169], v[82:85], v[34:49]
	s_waitcnt lgkmcnt(12)
	v_mfma_f32_32x32x16_bf16 v[34:49], v[170:173], v[86:89], v[34:49]
	s_waitcnt lgkmcnt(10)
	v_mfma_f32_32x32x16_bf16 v[34:49], v[174:177], v[90:93], v[34:49]
	s_waitcnt lgkmcnt(8)
	v_mfma_f32_32x32x16_bf16 v[34:49], v[178:181], v[94:97], v[34:49]
	s_setprio 0
	ds_read_b64_tr_b16 v[82:83], v197 offset:17920
	ds_read_b64_tr_b16 v[84:85], v197 offset:19968
	ds_read_b64_tr_b16 v[86:87], v197 offset:22016
	ds_read_b64_tr_b16 v[88:89], v197 offset:24064
	ds_read_b64_tr_b16 v[90:91], v197 offset:26112
	ds_read_b64_tr_b16 v[92:93], v197 offset:28160
	ds_read_b64_tr_b16 v[94:95], v197 offset:30208
	ds_read_b64_tr_b16 v[96:97], v197 offset:32256
	s_setprio 1
	s_waitcnt lgkmcnt(14)
	v_mfma_f32_32x32x16_bf16 v[50:65], v[166:169], v[66:69], v[50:65]
	s_waitcnt lgkmcnt(12)
	v_mfma_f32_32x32x16_bf16 v[50:65], v[170:173], v[70:73], v[50:65]
	s_waitcnt lgkmcnt(10)
	v_mfma_f32_32x32x16_bf16 v[50:65], v[174:177], v[74:77], v[50:65]
	s_waitcnt lgkmcnt(8)
	v_mfma_f32_32x32x16_bf16 v[50:65], v[178:181], v[78:81], v[50:65]
	s_setprio 0
	s_setprio 1
	s_waitcnt lgkmcnt(6)
	v_mfma_f32_32x32x16_bf16 v[2:17], v[166:169], v[82:85], v[2:17]
	s_waitcnt lgkmcnt(4)
	v_mfma_f32_32x32x16_bf16 v[2:17], v[170:173], v[86:89], v[2:17]
	s_waitcnt lgkmcnt(2)
	v_mfma_f32_32x32x16_bf16 v[2:17], v[174:177], v[90:93], v[2:17]
	s_waitcnt lgkmcnt(0)
	v_mfma_f32_32x32x16_bf16 v[2:17], v[178:181], v[94:97], v[2:17]
	s_barrier
	s_setprio 0
	s_waitcnt vmcnt(0)
	s_cmp_lt_i32 s11, -1
	s_cbranch_scc0 .LBB0_851
	v_add_u32_e32 v0, s82, v188
	s_waitcnt vmcnt(2)
	ds_write_b128 v0, v[146:149] offset:32768
	s_waitcnt vmcnt(1)
	ds_write_b128 v0, v[150:153] offset:45568
	v_add_u32_e32 v0, s82, v186
	s_waitcnt vmcnt(0)
	ds_write_b128 v0, v[154:157] offset:33024
